# v22 + static s_setprio 1 for waves 4-7 during ml_phase_c, reset at phase end
# speedup vs baseline: 1.0117x; 1.0030x over previous
; #define LAS __attribute__((address_space(3)))
; __device__ __forceinline__ Frame fresh(const Frame& F0) { Frame F = F0; int t = threadIdx.x; asm volatile("" : "+v"(t)); F.tid = t; F.lane = t & 63; F.wave = __builtin_amdgcn_readfirstlane(t >> 6); return F; }
; __device__ __forceinline__ void ml_phase_c(const Args& A, Frame& F0) {
;     Frame F = fresh(F0);
;     LAS unsigned char* Qs = F.lds; LAS unsigned char* Ks = F.lds + 9216; LAS unsigned char* Vs = F.lds + 18432; LAS unsigned char* Cs = F.lds + 35840;
;     LAS float* nvec = (LAS float*)(F.lds + 54272); LAS float* btv = (LAS float*)(F.lds + 54528); LAS float* biv = (LAS float*)(F.lds + 54784); LAS float* red = (LAS float*)(F.lds + 55040);
;     const bf16* PROJ = (const bf16*)(A.ws + WS_BIG); const bf16* QKC = (const bf16*)(A.ws + WS_QKC); const bf16* ST = (const bf16*)(A.ws + WS_ST);
;     const float* GB = (const float*)(A.ws + WS_GB); const float* GI = (const float*)(A.ws + WS_GI); const float* GSC = (const float*)(A.ws + WS_GSC); const float* NV = (const float*)(A.ws + WS_NV);
;     bf16* XN = (bf16*)(A.ws + WS_XN);
;     const int lane = F.lane, wave = F.wave, tid = F.tid;
;     const int rt = wave >> 2, vt = wave & 3, hh = lane >> 5, l31 = lane & 31, i16 = lane & 15, q = i16 >> 2, p = i16 & 3, blk = (lane >> 4) & 1;
;     LAS float* hg = (LAS float*)(F.lds + 57344);
;     for (int i = tid; i < 1024; i += NWAVES * 64) hg[i] = A.ml_hnorm_g[i];
;     __syncthreads();
.LBB0_1004:
	s_or_b64 exec, exec, s[4:5]
	v_mov_b32_e32 v2, v182
	s_movk_i32 s0, 0x400
	s_waitcnt lgkmcnt(0)
	s_barrier
	s_nop 0
	v_readfirstlane_b32 s10, v2
	s_nop 3
	s_cmpk_lt_u32 s10, 0x100
	s_cbranch_scc1 .Lmlc_prio_done
	s_setprio 1
.Lmlc_prio_done:
	v_cmp_gt_i32_e32 vcc, s0, v2
	s_and_saveexec_b64 s[0:1], vcc
	s_movk_i32 s6, 0x1ff
	s_cbranch_execz .LBB0_1017
	v_max_i32_e32 v0, 0x200, v2
	v_sub_u32_e32 v0, v0, v2
	v_add_u32_e32 v0, 0x1ff, v0
	v_cmp_lt_u32_e32 vcc, s6, v0
	s_mov_b64 s[6:7], -1
	v_mov_b32_e32 v4, v2
	s_and_saveexec_b64 s[4:5], vcc
	s_cbranch_execz .LBB0_1014
	v_lshrrev_b32_e32 v0, 9, v0
	v_add_u32_e32 v4, -1, v0
	v_add_u32_e32 v3, 0x200, v2
	v_lshrrev_b32_e32 v5, 1, v4
	v_add_u32_e32 v6, 1, v5
	v_cmp_lt_u32_e32 vcc, 13, v4
	v_mov_b32_e32 v9, 0
	v_mov_b64_e32 v[4:5], v[2:3]
	s_and_saveexec_b64 s[6:7], vcc
	s_cbranch_execz .LBB0_1010
	s_add_i32 s8, 0, 0xe000
	v_readlane_b32 s12, v253, 5
	v_and_b32_e32 v7, -8, v6
	v_lshl_add_u32 v8, v2, 2, s8
	s_mov_b32 s11, 0
	s_mov_b64 s[8:9], 0
	v_mov_b64_e32 v[4:5], v[2:3]
	v_readlane_b32 s18, v253, 11
	v_readlane_b32 s19, v253, 12
	v_readlane_b32 s13, v253, 6
	v_readlane_b32 s14, v253, 7
	v_readlane_b32 s15, v253, 8
	v_readlane_b32 s16, v253, 9
	v_readlane_b32 s17, v253, 10
	v_readlane_b32 s20, v253, 13
	v_readlane_b32 s21, v253, 14
	v_readlane_b32 s22, v253, 15
	v_readlane_b32 s23, v253, 16
	v_readlane_b32 s24, v253, 17
	v_readlane_b32 s25, v253, 18
	v_readlane_b32 s26, v253, 19
	v_readlane_b32 s27, v253, 20

; __device__ __forceinline__ unsigned xb_add(unsigned* p, unsigned v) { return __hip_atomic_fetch_add(p, v, __ATOMIC_RELAXED, __HIP_MEMORY_SCOPE_AGENT); }
; __device__ __forceinline__ void xcd_barrier(const XcdBarrier& b) {
;     asm volatile("s_waitcnt vmcnt(0)" ::: "memory");
;     __syncthreads();
;     if (threadIdx.x == 0) {
;         unsigned* bar = b.bar;
;         __builtin_amdgcn_s_waitcnt(0);
;         unsigned nloc = b.st[0], nx = b.st[1];
;         if (nloc == 0u) { xcd_barrier_complete(bar, b.x, nloc, nx); b.st[0] = nloc; b.st[1] = nx; }
;         const unsigned old = xb_add(&bar[XB_XSUB(b.x)], 1u);
;         const unsigned gen = old / nloc;
;         if (old + 1u == (gen + 1u) * nloc) {
.LBB0_1032:
	s_setprio 0
	v_readlane_b32 s44, v253, 0
	v_readlane_b32 s33, v253, 2
	v_readlane_b32 s45, v253, 1
	s_waitcnt vmcnt(0)
	s_barrier
	s_mov_b64 s[4:5], exec
	v_readlane_b32 s0, v253, 3
	v_readlane_b32 s1, v253, 4
	s_and_b64 s[0:1], s[4:5], s[0:1]
	s_mov_b64 exec, s[0:1]
	s_cbranch_execz .LBB0_1076
	v_readlane_b32 s0, v254, 51
	s_waitcnt vmcnt(0) expcnt(0) lgkmcnt(0)
	s_nop 0
	v_mov_b32_e32 v0, s0
	ds_read_b32 v2, v0
	v_readlane_b32 s0, v254, 52
	s_waitcnt lgkmcnt(0)
	v_cmp_ne_u32_e32 vcc, 0, v2
	v_mov_b32_e32 v0, s0
	ds_read_b32 v0, v0
	s_cbranch_vccnz .LBB0_1047
	s_add_u32 s0, s44, 0x1000
	s_addc_u32 s1, s45, 0
	s_add_u32 s6, s44, 0x1100
	s_addc_u32 s7, s45, 0
	s_add_u32 s8, s44, 0x1200
	s_addc_u32 s9, s45, 0
	s_add_u32 s10, s44, 0x1300
	s_addc_u32 s11, s45, 0
	s_mov_b32 s30, 1
	s_mov_b64 s[12:13], 0
	s_branch .LBB0_1037
